# G5 SwiGLU epilogue rewritten with packed f32 ops in the baseline's operation order (same results): 8 independent chains per store, 386 instead of 666 lines, no hazard s_nops
# speedup vs baseline: 1.0060x; 1.0040x over previous
.LBB0_1801:
	s_waitcnt vmcnt(8)
	v_lshl_add_u32 v186, s9, 8, v1
	v_lshl_or_b32 v184, s8, 7, v143
	v_readlane_b32 s8, v245, 21
	v_readlane_b32 s9, v245, 22
	v_ashrrev_i32_e32 v185, 31, v184
	s_movk_i32 s5, 0x2c00
	v_lshlrev_b64 v[184:185], 1, v[184:185]
	v_mov_b64_e32 v[182:183], s[8:9]
	v_mov_b32_e32 v188, 0x2c000
	v_mad_i64_i32 v[180:181], vcc, v186, s5, v[182:183]
	v_mov_b32_e32 v189, 0
	s_mov_b64 s[22:23], -1
	v_lshl_add_u64 v[180:181], v[180:181], 0, v[184:185]
	v_mov_b32_e32 v190, 0xdc000
	v_mov_b32_e32 v191, 0
	v_mov_b32_e32 v192, 0xbfb8aa3b
	s_mov_b32 s26, 0x2aaaaaab
	v_pk_mul_f32 v[126:127], v[158:159], v[126:127] op_sel_hi:[0,1]
	v_pk_mul_f32 v[128:129], v[158:159], v[128:129] op_sel_hi:[0,1]
	v_pk_mul_f32 v[122:123], v[158:159], v[122:123] op_sel_hi:[0,1]
	v_pk_mul_f32 v[124:125], v[158:159], v[124:125] op_sel_hi:[0,1]
	v_pk_mul_f32 v[118:119], v[158:159], v[118:119] op_sel_hi:[0,1]
	v_pk_mul_f32 v[120:121], v[158:159], v[120:121] op_sel_hi:[0,1]
	v_pk_mul_f32 v[114:115], v[158:159], v[114:115] op_sel_hi:[0,1]
	v_pk_mul_f32 v[116:117], v[158:159], v[116:117] op_sel_hi:[0,1]
	v_pk_mul_f32 v[118:119], v[126:127], v[118:119]
	v_pk_mul_f32 v[120:121], v[128:129], v[120:121]
	v_pk_mul_f32 v[114:115], v[122:123], v[114:115]
	v_pk_mul_f32 v[116:117], v[124:125], v[116:117]
	v_pk_mul_f32 v[126:127], v[126:127], v[192:193] op_sel_hi:[1,0]
	v_pk_mul_f32 v[128:129], v[128:129], v[192:193] op_sel_hi:[1,0]
	v_pk_mul_f32 v[122:123], v[122:123], v[192:193] op_sel_hi:[1,0]
	v_pk_mul_f32 v[124:125], v[124:125], v[192:193] op_sel_hi:[1,0]
	v_exp_f32_e32 v126, v126
	v_exp_f32_e32 v127, v127
	v_exp_f32_e32 v128, v128
	v_exp_f32_e32 v129, v129
	v_exp_f32_e32 v122, v122
	v_exp_f32_e32 v123, v123
	v_exp_f32_e32 v124, v124
	v_exp_f32_e32 v125, v125
	v_pk_add_f32 v[126:127], v[126:127], 1.0 op_sel_hi:[1,0]
	v_pk_add_f32 v[128:129], v[128:129], 1.0 op_sel_hi:[1,0]
	v_pk_add_f32 v[122:123], v[122:123], 1.0 op_sel_hi:[1,0]
	v_pk_add_f32 v[124:125], v[124:125], 1.0 op_sel_hi:[1,0]
	v_rcp_f32_e32 v126, v126
	v_rcp_f32_e32 v127, v127
	v_rcp_f32_e32 v128, v128
	v_rcp_f32_e32 v129, v129
	v_rcp_f32_e32 v122, v122
	v_rcp_f32_e32 v123, v123
	v_rcp_f32_e32 v124, v124
	v_rcp_f32_e32 v125, v125
	v_pk_mul_f32 v[118:119], v[126:127], v[118:119]
	v_pk_mul_f32 v[120:121], v[128:129], v[120:121]
	v_pk_mul_f32 v[114:115], v[122:123], v[114:115]
	v_pk_mul_f32 v[116:117], v[124:125], v[116:117]
	v_cvt_pk_bf16_f32 v126, v118, v119
	v_cvt_pk_bf16_f32 v127, v120, v121
	v_cvt_pk_bf16_f32 v128, v114, v115
	v_cvt_pk_bf16_f32 v129, v116, v117
	global_store_dwordx4 v[180:181], v[126:129], off
	v_lshl_add_u64 v[180:181], v[180:181], 0, v[188:189]
	v_pk_mul_f32 v[110:111], v[156:157], v[110:111] op_sel_hi:[0,1]
	v_pk_mul_f32 v[112:113], v[156:157], v[112:113] op_sel_hi:[0,1]
	v_pk_mul_f32 v[106:107], v[156:157], v[106:107] op_sel_hi:[0,1]
	v_pk_mul_f32 v[108:109], v[156:157], v[108:109] op_sel_hi:[0,1]
	v_pk_mul_f32 v[102:103], v[156:157], v[102:103] op_sel_hi:[0,1]
	v_pk_mul_f32 v[104:105], v[156:157], v[104:105] op_sel_hi:[0,1]
	v_pk_mul_f32 v[98:99], v[156:157], v[98:99] op_sel_hi:[0,1]
	v_pk_mul_f32 v[100:101], v[156:157], v[100:101] op_sel_hi:[0,1]
	v_pk_mul_f32 v[102:103], v[110:111], v[102:103]
	v_pk_mul_f32 v[104:105], v[112:113], v[104:105]
	v_pk_mul_f32 v[98:99], v[106:107], v[98:99]
	v_pk_mul_f32 v[100:101], v[108:109], v[100:101]
	v_pk_mul_f32 v[110:111], v[110:111], v[192:193] op_sel_hi:[1,0]
	v_pk_mul_f32 v[112:113], v[112:113], v[192:193] op_sel_hi:[1,0]
	v_pk_mul_f32 v[106:107], v[106:107], v[192:193] op_sel_hi:[1,0]
	v_pk_mul_f32 v[108:109], v[108:109], v[192:193] op_sel_hi:[1,0]
	v_exp_f32_e32 v110, v110
	v_exp_f32_e32 v111, v111
	v_exp_f32_e32 v112, v112
	v_exp_f32_e32 v113, v113
	v_exp_f32_e32 v106, v106
	v_exp_f32_e32 v107, v107
	v_exp_f32_e32 v108, v108
	v_exp_f32_e32 v109, v109
	v_pk_add_f32 v[110:111], v[110:111], 1.0 op_sel_hi:[1,0]
	v_pk_add_f32 v[112:113], v[112:113], 1.0 op_sel_hi:[1,0]
	v_pk_add_f32 v[106:107], v[106:107], 1.0 op_sel_hi:[1,0]
	v_pk_add_f32 v[108:109], v[108:109], 1.0 op_sel_hi:[1,0]
	v_rcp_f32_e32 v110, v110
	v_rcp_f32_e32 v111, v111
	v_rcp_f32_e32 v112, v112
	v_rcp_f32_e32 v113, v113
	v_rcp_f32_e32 v106, v106
	v_rcp_f32_e32 v107, v107
	v_rcp_f32_e32 v108, v108
	v_rcp_f32_e32 v109, v109
	v_pk_mul_f32 v[102:103], v[110:111], v[102:103]
	v_pk_mul_f32 v[104:105], v[112:113], v[104:105]
	v_pk_mul_f32 v[98:99], v[106:107], v[98:99]
	v_pk_mul_f32 v[100:101], v[108:109], v[100:101]
	v_cvt_pk_bf16_f32 v110, v102, v103
	v_cvt_pk_bf16_f32 v111, v104, v105
	v_cvt_pk_bf16_f32 v112, v98, v99
	v_cvt_pk_bf16_f32 v113, v100, v101
	global_store_dwordx4 v[180:181], v[110:113], off
	v_lshl_add_u64 v[180:181], v[180:181], 0, v[188:189]
	v_pk_mul_f32 v[94:95], v[150:151], v[94:95] op_sel_hi:[0,1]
	v_pk_mul_f32 v[96:97], v[150:151], v[96:97] op_sel_hi:[0,1]
	v_pk_mul_f32 v[90:91], v[150:151], v[90:91] op_sel_hi:[0,1]
	v_pk_mul_f32 v[92:93], v[150:151], v[92:93] op_sel_hi:[0,1]
	v_pk_mul_f32 v[86:87], v[150:151], v[86:87] op_sel_hi:[0,1]
	v_pk_mul_f32 v[88:89], v[150:151], v[88:89] op_sel_hi:[0,1]
	v_pk_mul_f32 v[82:83], v[150:151], v[82:83] op_sel_hi:[0,1]
	v_pk_mul_f32 v[84:85], v[150:151], v[84:85] op_sel_hi:[0,1]
	v_pk_mul_f32 v[86:87], v[94:95], v[86:87]
	v_pk_mul_f32 v[88:89], v[96:97], v[88:89]
	v_pk_mul_f32 v[82:83], v[90:91], v[82:83]
	v_pk_mul_f32 v[84:85], v[92:93], v[84:85]
	v_pk_mul_f32 v[94:95], v[94:95], v[192:193] op_sel_hi:[1,0]
	v_pk_mul_f32 v[96:97], v[96:97], v[192:193] op_sel_hi:[1,0]
	v_pk_mul_f32 v[90:91], v[90:91], v[192:193] op_sel_hi:[1,0]
	v_pk_mul_f32 v[92:93], v[92:93], v[192:193] op_sel_hi:[1,0]
	v_exp_f32_e32 v94, v94
	v_exp_f32_e32 v95, v95
	v_exp_f32_e32 v96, v96
	v_exp_f32_e32 v97, v97
	v_exp_f32_e32 v90, v90
	v_exp_f32_e32 v91, v91
	v_exp_f32_e32 v92, v92
	v_exp_f32_e32 v93, v93
	v_pk_add_f32 v[94:95], v[94:95], 1.0 op_sel_hi:[1,0]
	v_pk_add_f32 v[96:97], v[96:97], 1.0 op_sel_hi:[1,0]
	v_pk_add_f32 v[90:91], v[90:91], 1.0 op_sel_hi:[1,0]
	v_pk_add_f32 v[92:93], v[92:93], 1.0 op_sel_hi:[1,0]
	v_rcp_f32_e32 v94, v94
	v_rcp_f32_e32 v95, v95
	v_rcp_f32_e32 v96, v96
	v_rcp_f32_e32 v97, v97
	v_rcp_f32_e32 v90, v90
	v_rcp_f32_e32 v91, v91
	v_rcp_f32_e32 v92, v92
	v_rcp_f32_e32 v93, v93
	v_pk_mul_f32 v[86:87], v[94:95], v[86:87]
	v_pk_mul_f32 v[88:89], v[96:97], v[88:89]
	v_pk_mul_f32 v[82:83], v[90:91], v[82:83]
	v_pk_mul_f32 v[84:85], v[92:93], v[84:85]
	v_cvt_pk_bf16_f32 v94, v86, v87
	v_cvt_pk_bf16_f32 v95, v88, v89
	v_cvt_pk_bf16_f32 v96, v82, v83
	v_cvt_pk_bf16_f32 v97, v84, v85
	global_store_dwordx4 v[180:181], v[94:97], off
	v_lshl_add_u64 v[180:181], v[180:181], 0, v[188:189]
	v_pk_mul_f32 v[78:79], v[148:149], v[78:79] op_sel_hi:[0,1]
	v_pk_mul_f32 v[80:81], v[148:149], v[80:81] op_sel_hi:[0,1]
	v_pk_mul_f32 v[74:75], v[148:149], v[74:75] op_sel_hi:[0,1]
	v_pk_mul_f32 v[76:77], v[148:149], v[76:77] op_sel_hi:[0,1]
	v_pk_mul_f32 v[70:71], v[148:149], v[70:71] op_sel_hi:[0,1]
	v_pk_mul_f32 v[72:73], v[148:149], v[72:73] op_sel_hi:[0,1]
	v_pk_mul_f32 v[66:67], v[148:149], v[66:67] op_sel_hi:[0,1]
	v_pk_mul_f32 v[68:69], v[148:149], v[68:69] op_sel_hi:[0,1]
	v_pk_mul_f32 v[70:71], v[78:79], v[70:71]
	v_pk_mul_f32 v[72:73], v[80:81], v[72:73]
	v_pk_mul_f32 v[66:67], v[74:75], v[66:67]
	v_pk_mul_f32 v[68:69], v[76:77], v[68:69]
	v_pk_mul_f32 v[78:79], v[78:79], v[192:193] op_sel_hi:[1,0]
	v_pk_mul_f32 v[80:81], v[80:81], v[192:193] op_sel_hi:[1,0]
	v_pk_mul_f32 v[74:75], v[74:75], v[192:193] op_sel_hi:[1,0]
	v_pk_mul_f32 v[76:77], v[76:77], v[192:193] op_sel_hi:[1,0]
	v_exp_f32_e32 v78, v78
	v_exp_f32_e32 v79, v79
	v_exp_f32_e32 v80, v80
	v_exp_f32_e32 v81, v81
	v_exp_f32_e32 v74, v74
	v_exp_f32_e32 v75, v75
	v_exp_f32_e32 v76, v76
	v_exp_f32_e32 v77, v77
	v_pk_add_f32 v[78:79], v[78:79], 1.0 op_sel_hi:[1,0]
	v_pk_add_f32 v[80:81], v[80:81], 1.0 op_sel_hi:[1,0]
	v_pk_add_f32 v[74:75], v[74:75], 1.0 op_sel_hi:[1,0]
	v_pk_add_f32 v[76:77], v[76:77], 1.0 op_sel_hi:[1,0]
	v_rcp_f32_e32 v78, v78
	v_rcp_f32_e32 v79, v79
	v_rcp_f32_e32 v80, v80
	v_rcp_f32_e32 v81, v81
	v_rcp_f32_e32 v74, v74
	v_rcp_f32_e32 v75, v75
	v_rcp_f32_e32 v76, v76
	v_rcp_f32_e32 v77, v77
	v_pk_mul_f32 v[70:71], v[78:79], v[70:71]
	v_pk_mul_f32 v[72:73], v[80:81], v[72:73]
	v_pk_mul_f32 v[66:67], v[74:75], v[66:67]
	v_pk_mul_f32 v[68:69], v[76:77], v[68:69]
	v_cvt_pk_bf16_f32 v78, v70, v71
	v_cvt_pk_bf16_f32 v79, v72, v73
	v_cvt_pk_bf16_f32 v80, v66, v67
	v_cvt_pk_bf16_f32 v81, v68, v69
	global_store_dwordx4 v[180:181], v[78:81], off
	v_lshl_add_u64 v[180:181], v[180:181], 0, v[190:191]
	v_pk_mul_f32 v[62:63], v[146:147], v[62:63] op_sel_hi:[0,1]
	v_pk_mul_f32 v[64:65], v[146:147], v[64:65] op_sel_hi:[0,1]
	v_pk_mul_f32 v[58:59], v[146:147], v[58:59] op_sel_hi:[0,1]
	v_pk_mul_f32 v[60:61], v[146:147], v[60:61] op_sel_hi:[0,1]
	v_pk_mul_f32 v[54:55], v[146:147], v[54:55] op_sel_hi:[0,1]
	v_pk_mul_f32 v[56:57], v[146:147], v[56:57] op_sel_hi:[0,1]
	v_pk_mul_f32 v[50:51], v[146:147], v[50:51] op_sel_hi:[0,1]
	v_pk_mul_f32 v[52:53], v[146:147], v[52:53] op_sel_hi:[0,1]
	v_pk_mul_f32 v[54:55], v[62:63], v[54:55]
	v_pk_mul_f32 v[56:57], v[64:65], v[56:57]
	v_pk_mul_f32 v[50:51], v[58:59], v[50:51]
	v_pk_mul_f32 v[52:53], v[60:61], v[52:53]
	v_pk_mul_f32 v[62:63], v[62:63], v[192:193] op_sel_hi:[1,0]
	v_pk_mul_f32 v[64:65], v[64:65], v[192:193] op_sel_hi:[1,0]
	v_pk_mul_f32 v[58:59], v[58:59], v[192:193] op_sel_hi:[1,0]
	v_pk_mul_f32 v[60:61], v[60:61], v[192:193] op_sel_hi:[1,0]
	v_exp_f32_e32 v62, v62
	v_exp_f32_e32 v63, v63
	v_exp_f32_e32 v64, v64
	v_exp_f32_e32 v65, v65
	v_exp_f32_e32 v58, v58
	v_exp_f32_e32 v59, v59
	v_exp_f32_e32 v60, v60
	v_exp_f32_e32 v61, v61
	v_pk_add_f32 v[62:63], v[62:63], 1.0 op_sel_hi:[1,0]
	v_pk_add_f32 v[64:65], v[64:65], 1.0 op_sel_hi:[1,0]
	v_pk_add_f32 v[58:59], v[58:59], 1.0 op_sel_hi:[1,0]
	v_pk_add_f32 v[60:61], v[60:61], 1.0 op_sel_hi:[1,0]
	v_rcp_f32_e32 v62, v62
	v_rcp_f32_e32 v63, v63
	v_rcp_f32_e32 v64, v64
	v_rcp_f32_e32 v65, v65
	v_rcp_f32_e32 v58, v58
	v_rcp_f32_e32 v59, v59
	v_rcp_f32_e32 v60, v60
	v_rcp_f32_e32 v61, v61
	v_pk_mul_f32 v[54:55], v[62:63], v[54:55]
	v_pk_mul_f32 v[56:57], v[64:65], v[56:57]
	v_pk_mul_f32 v[50:51], v[58:59], v[50:51]
	v_pk_mul_f32 v[52:53], v[60:61], v[52:53]
	v_cvt_pk_bf16_f32 v62, v54, v55
	v_cvt_pk_bf16_f32 v63, v56, v57
	v_cvt_pk_bf16_f32 v64, v50, v51
	v_cvt_pk_bf16_f32 v65, v52, v53
	global_store_dwordx4 v[180:181], v[62:65], off
	v_lshl_add_u64 v[180:181], v[180:181], 0, v[188:189]
	v_pk_mul_f32 v[46:47], v[144:145], v[46:47] op_sel_hi:[0,1]
	v_pk_mul_f32 v[48:49], v[144:145], v[48:49] op_sel_hi:[0,1]
	v_pk_mul_f32 v[42:43], v[144:145], v[42:43] op_sel_hi:[0,1]
	v_pk_mul_f32 v[44:45], v[144:145], v[44:45] op_sel_hi:[0,1]
	v_pk_mul_f32 v[38:39], v[144:145], v[38:39] op_sel_hi:[0,1]
	v_pk_mul_f32 v[40:41], v[144:145], v[40:41] op_sel_hi:[0,1]
	v_pk_mul_f32 v[34:35], v[144:145], v[34:35] op_sel_hi:[0,1]
	v_pk_mul_f32 v[36:37], v[144:145], v[36:37] op_sel_hi:[0,1]
	v_pk_mul_f32 v[38:39], v[46:47], v[38:39]
	v_pk_mul_f32 v[40:41], v[48:49], v[40:41]
	v_pk_mul_f32 v[34:35], v[42:43], v[34:35]
	v_pk_mul_f32 v[36:37], v[44:45], v[36:37]
	v_pk_mul_f32 v[46:47], v[46:47], v[192:193] op_sel_hi:[1,0]
	v_pk_mul_f32 v[48:49], v[48:49], v[192:193] op_sel_hi:[1,0]
	v_pk_mul_f32 v[42:43], v[42:43], v[192:193] op_sel_hi:[1,0]
	v_pk_mul_f32 v[44:45], v[44:45], v[192:193] op_sel_hi:[1,0]
	v_exp_f32_e32 v46, v46
	v_exp_f32_e32 v47, v47
	v_exp_f32_e32 v48, v48
	v_exp_f32_e32 v49, v49
	v_exp_f32_e32 v42, v42
	v_exp_f32_e32 v43, v43
	v_exp_f32_e32 v44, v44
	v_exp_f32_e32 v45, v45
	v_pk_add_f32 v[46:47], v[46:47], 1.0 op_sel_hi:[1,0]
	v_pk_add_f32 v[48:49], v[48:49], 1.0 op_sel_hi:[1,0]
	v_pk_add_f32 v[42:43], v[42:43], 1.0 op_sel_hi:[1,0]
	v_pk_add_f32 v[44:45], v[44:45], 1.0 op_sel_hi:[1,0]
	v_rcp_f32_e32 v46, v46
	v_rcp_f32_e32 v47, v47
	v_rcp_f32_e32 v48, v48
	v_rcp_f32_e32 v49, v49
	v_rcp_f32_e32 v42, v42
	v_rcp_f32_e32 v43, v43
	v_rcp_f32_e32 v44, v44
	v_rcp_f32_e32 v45, v45
	v_pk_mul_f32 v[38:39], v[46:47], v[38:39]
	v_pk_mul_f32 v[40:41], v[48:49], v[40:41]
	v_pk_mul_f32 v[34:35], v[42:43], v[34:35]
	v_pk_mul_f32 v[36:37], v[44:45], v[36:37]
	v_cvt_pk_bf16_f32 v46, v38, v39
	v_cvt_pk_bf16_f32 v47, v40, v41
	v_cvt_pk_bf16_f32 v48, v34, v35
	v_cvt_pk_bf16_f32 v49, v36, v37
	global_store_dwordx4 v[180:181], v[46:49], off
	v_lshl_add_u64 v[180:181], v[180:181], 0, v[188:189]
	v_pk_mul_f32 v[30:31], v[142:143], v[30:31] op_sel_hi:[0,1]
	v_pk_mul_f32 v[32:33], v[142:143], v[32:33] op_sel_hi:[0,1]
	v_pk_mul_f32 v[26:27], v[142:143], v[26:27] op_sel_hi:[0,1]
	v_pk_mul_f32 v[28:29], v[142:143], v[28:29] op_sel_hi:[0,1]
	v_pk_mul_f32 v[22:23], v[142:143], v[22:23] op_sel_hi:[0,1]
	v_pk_mul_f32 v[24:25], v[142:143], v[24:25] op_sel_hi:[0,1]
	v_pk_mul_f32 v[18:19], v[142:143], v[18:19] op_sel_hi:[0,1]
	v_pk_mul_f32 v[20:21], v[142:143], v[20:21] op_sel_hi:[0,1]
	v_pk_mul_f32 v[22:23], v[30:31], v[22:23]
	v_pk_mul_f32 v[24:25], v[32:33], v[24:25]
	v_pk_mul_f32 v[18:19], v[26:27], v[18:19]
	v_pk_mul_f32 v[20:21], v[28:29], v[20:21]
	v_pk_mul_f32 v[30:31], v[30:31], v[192:193] op_sel_hi:[1,0]
	v_pk_mul_f32 v[32:33], v[32:33], v[192:193] op_sel_hi:[1,0]
	v_pk_mul_f32 v[26:27], v[26:27], v[192:193] op_sel_hi:[1,0]
	v_pk_mul_f32 v[28:29], v[28:29], v[192:193] op_sel_hi:[1,0]
	v_exp_f32_e32 v30, v30
	v_exp_f32_e32 v31, v31
	v_exp_f32_e32 v32, v32
	v_exp_f32_e32 v33, v33
	v_exp_f32_e32 v26, v26
	v_exp_f32_e32 v27, v27
	v_exp_f32_e32 v28, v28
	v_exp_f32_e32 v29, v29
	v_pk_add_f32 v[30:31], v[30:31], 1.0 op_sel_hi:[1,0]
	v_pk_add_f32 v[32:33], v[32:33], 1.0 op_sel_hi:[1,0]
	v_pk_add_f32 v[26:27], v[26:27], 1.0 op_sel_hi:[1,0]
	v_pk_add_f32 v[28:29], v[28:29], 1.0 op_sel_hi:[1,0]
	v_rcp_f32_e32 v30, v30
	v_rcp_f32_e32 v31, v31
	v_rcp_f32_e32 v32, v32
	v_rcp_f32_e32 v33, v33
	v_rcp_f32_e32 v26, v26
	v_rcp_f32_e32 v27, v27
	v_rcp_f32_e32 v28, v28
	v_rcp_f32_e32 v29, v29
	v_pk_mul_f32 v[22:23], v[30:31], v[22:23]
	v_pk_mul_f32 v[24:25], v[32:33], v[24:25]
	v_pk_mul_f32 v[18:19], v[26:27], v[18:19]
	v_pk_mul_f32 v[20:21], v[28:29], v[20:21]
	v_cvt_pk_bf16_f32 v30, v22, v23
	v_cvt_pk_bf16_f32 v31, v24, v25
	v_cvt_pk_bf16_f32 v32, v18, v19
	v_cvt_pk_bf16_f32 v33, v20, v21
	global_store_dwordx4 v[180:181], v[30:33], off
	v_lshl_add_u64 v[180:181], v[180:181], 0, v[188:189]
	v_pk_mul_f32 v[14:15], v[140:141], v[14:15] op_sel_hi:[0,1]
	v_pk_mul_f32 v[16:17], v[140:141], v[16:17] op_sel_hi:[0,1]
	v_pk_mul_f32 v[10:11], v[140:141], v[10:11] op_sel_hi:[0,1]
	v_pk_mul_f32 v[12:13], v[140:141], v[12:13] op_sel_hi:[0,1]
	v_pk_mul_f32 v[6:7], v[140:141], v[6:7] op_sel_hi:[0,1]
	v_pk_mul_f32 v[8:9], v[140:141], v[8:9] op_sel_hi:[0,1]
	v_pk_mul_f32 v[2:3], v[140:141], v[2:3] op_sel_hi:[0,1]
	v_pk_mul_f32 v[4:5], v[140:141], v[4:5] op_sel_hi:[0,1]
	v_pk_mul_f32 v[6:7], v[14:15], v[6:7]
	v_pk_mul_f32 v[8:9], v[16:17], v[8:9]
	v_pk_mul_f32 v[2:3], v[10:11], v[2:3]
	v_pk_mul_f32 v[4:5], v[12:13], v[4:5]
	v_pk_mul_f32 v[14:15], v[14:15], v[192:193] op_sel_hi:[1,0]
	v_pk_mul_f32 v[16:17], v[16:17], v[192:193] op_sel_hi:[1,0]
	v_pk_mul_f32 v[10:11], v[10:11], v[192:193] op_sel_hi:[1,0]
	v_pk_mul_f32 v[12:13], v[12:13], v[192:193] op_sel_hi:[1,0]
	v_exp_f32_e32 v14, v14
	v_exp_f32_e32 v15, v15
	v_exp_f32_e32 v16, v16
	v_exp_f32_e32 v17, v17
	v_exp_f32_e32 v10, v10
	v_exp_f32_e32 v11, v11
	v_exp_f32_e32 v12, v12
	v_exp_f32_e32 v13, v13
	v_pk_add_f32 v[14:15], v[14:15], 1.0 op_sel_hi:[1,0]
	v_pk_add_f32 v[16:17], v[16:17], 1.0 op_sel_hi:[1,0]
	v_pk_add_f32 v[10:11], v[10:11], 1.0 op_sel_hi:[1,0]
	v_pk_add_f32 v[12:13], v[12:13], 1.0 op_sel_hi:[1,0]
	v_rcp_f32_e32 v14, v14
	v_rcp_f32_e32 v15, v15
	v_rcp_f32_e32 v16, v16
	v_rcp_f32_e32 v17, v17
	v_rcp_f32_e32 v10, v10
	v_rcp_f32_e32 v11, v11
	v_rcp_f32_e32 v12, v12
	v_rcp_f32_e32 v13, v13
	v_pk_mul_f32 v[6:7], v[14:15], v[6:7]
	v_pk_mul_f32 v[8:9], v[16:17], v[8:9]
	v_pk_mul_f32 v[2:3], v[10:11], v[2:3]
	v_pk_mul_f32 v[4:5], v[12:13], v[4:5]
	v_cvt_pk_bf16_f32 v14, v6, v7
	v_cvt_pk_bf16_f32 v15, v8, v9
	v_cvt_pk_bf16_f32 v16, v2, v3
	v_cvt_pk_bf16_f32 v17, v4, v5
	global_store_dwordx4 v[180:181], v[14:17], off
	s_andn2_b64 vcc, exec, s[34:35]
	s_cbranch_vccnz .LBB0_1794
	s_nop 0
	v_lshl_add_u32 v2, s18, 8, v1
	v_readlane_b32 s8, v245, 16
	v_ashrrev_i32_e32 v3, 31, v2
	v_readlane_b32 s9, v245, 17
	s_andn2_b64 vcc, exec, s[0:1]
	s_nop 0
	v_lshl_add_u64 v[2:3], v[2:3], 2, s[8:9]
	global_load_dword v158, v[2:3], off
	global_load_dword v156, v[2:3], off offset:64
	global_load_dword v150, v[2:3], off offset:128
	global_load_dword v148, v[2:3], off offset:192
	global_load_dword v146, v[2:3], off offset:512
	global_load_dword v144, v[2:3], off offset:576
	global_load_dword v142, v[2:3], off offset:640
	global_load_dword v140, v[2:3], off offset:704
	s_cbranch_vccnz .LBB0_1793
	s_barrier
	s_branch .LBB0_1793
